# PA-waves4-7-issue-tile-DMAs-mid-tile
# baseline (speedup 1.0000x reference)
; #define LAS __attribute__((address_space(3)))
; #define PA_BAR() do { asm volatile("s_waitcnt lgkmcnt(0)" ::: "memory"); __builtin_amdgcn_s_barrier(); asm volatile("" ::: "memory"); } while (0)
; __device__ __forceinline__ void issue_tile(const bf16* Kg, const bf16* Vg, LAS unsigned char* slot, int kv0, int wave, int lane) {
;     const unsigned s0 = (unsigned)(uintptr_t)slot;
;     { const bf16* src = Kg + (size_t)(kv0 + lane) * 768 + wave * 8;
;       glds16(src, (unsigned)__builtin_amdgcn_readfirstlane(s0 + wave * 1024));
;       if (wave < 4) glds16(src + 64, (unsigned)__builtin_amdgcn_readfirstlane(s0 + (8 + wave) * 1024)); }
;     { const bf16* src = Vg + (size_t)(kv0 + 16 * (wave & 3) + (lane >> 2)) * 1024 + (wave >> 2) * 32 + (lane & 3) * 8;
;       glds16(src, (unsigned)__builtin_amdgcn_readfirstlane(s0 + KSLOT + wave * 1024)); }
; }
; __device__ __forceinline__ void attn_unit(const bf16* Q, const bf16* K, const bf16* V, bf16* O, int b, int h, int qb, float sref, LAS unsigned char* lds, int wave, int lane_) {
;     ...
;     for (int t = 0; ; t += 2) {
;         const int s2 = (s1 == 2) ? 0 : s1 + 1;
;         asm volatile("s_waitcnt vmcnt(0)" ::: "memory"); PA_BAR();
;         if (t + 2 < NT) issue_tile(Kg, Vg, lds + s2 * SLOT, (t + 2) * 64, wave, lane);
.Lpa1_A_join:
	s_add_i32 s22, s83, 1
	s_cmp_lg_u32 s83, 2
	s_cselect_b32 s75, s22, 0
	s_waitcnt lgkmcnt(0)
	s_barrier
	s_add_i32 s82, s72, -1
	s_cmp_lt_u32 s82, s73
	s_cselect_b64 s[52:53], -1, 0
	s_cmp_ge_u32 s82, s73
	s_mul_i32 s85, s75, 0x5000
	s_cbranch_scc1 .LBB0_1404
	s_and_b64 vcc, exec, s[2:3]
	s_cbranch_vccnz .LBB0_1404
	v_add_u32_e32 v18, s74, v159
	s_add_i32 s22, s85, 0
	v_add_u32_e32 v18, 0xc0, v18
	v_mov_b64_e32 v[20:21], s[48:49]
	v_mad_i64_i32 v[20:21], s[86:87], v18, s65, v[20:21]
	s_add_i32 s22, s59, s22
	s_mul_i32 s98, s84, 0x5000
	s_add_i32 s98, s98, s59
	s_mov_b32 s86, m0
	s_mov_b32 m0, s98
	s_nop 0
	global_load_lds_dwordx4 v[20:21], off
	s_mov_b32 m0, s86
	s_and_b64 vcc, exec, s[2:3]
	s_cbranch_vccnz .LBB0_1403
	v_lshl_add_u64 v[20:21], v[20:21], 0, s[30:31]
	s_add_i32 s86, s98, 0x2000
	s_mov_b32 s87, m0
	s_mov_b32 m0, s86
	s_nop 0
	global_load_lds_dwordx4 v[20:21], off
	s_mov_b32 m0, s87

; #define LAS __attribute__((address_space(3)))
; __device__ __forceinline__ void issue_tile(const bf16* Kg, const bf16* Vg, LAS unsigned char* slot, int kv0, int wave, int lane) {
;     const unsigned s0 = (unsigned)(uintptr_t)slot;
;     { const bf16* src = Kg + (size_t)(kv0 + lane) * 768 + wave * 8;
;       glds16(src, (unsigned)__builtin_amdgcn_readfirstlane(s0 + wave * 1024));
;       if (wave < 4) glds16(src + 64, (unsigned)__builtin_amdgcn_readfirstlane(s0 + (8 + wave) * 1024)); }
;     { const bf16* src = Vg + (size_t)(kv0 + 16 * (wave & 3) + (lane >> 2)) * 1024 + (wave >> 2) * 32 + (lane & 3) * 8;
;       glds16(src, (unsigned)__builtin_amdgcn_readfirstlane(s0 + KSLOT + wave * 1024)); }
; }
.LBB0_1406:
	s_and_b64 vcc, exec, s[2:3]
	s_cbranch_vccz .Lpas1_1
	s_cmp_lt_u32 s82, s73
	s_cbranch_scc0 .Lpas1_1
	v_add_u32_e32 v228, s74, v159
	v_add_u32_e32 v228, 0xc0, v228
	v_mov_b64_e32 v[230:231], s[48:49]
	v_mad_i64_i32 v[230:231], s[100:101], v228, s65, v[230:231]
	s_mul_i32 s98, s84, 0x5000
	s_add_i32 s98, s98, s59
	s_mov_b32 s99, m0
	s_mov_b32 m0, s98
	s_nop 0
	global_load_lds_dwordx4 v[230:231], off
	s_mul_i32 s98, s75, 0x5000
	s_add_i32 s98, s98, s59
	s_addk_i32 s98, 0x3000
	s_mov_b32 m0, s98
	s_nop 0
	global_load_lds_dwordx4 v[162:163], off
	s_mov_b32 m0, s99

; #define LAS __attribute__((address_space(3)))
; #define PA_BAR() do { asm volatile("s_waitcnt lgkmcnt(0)" ::: "memory"); __builtin_amdgcn_s_barrier(); asm volatile("" ::: "memory"); } while (0)
; __device__ __forceinline__ void issue_tile(const bf16* Kg, const bf16* Vg, LAS unsigned char* slot, int kv0, int wave, int lane) {
;     const unsigned s0 = (unsigned)(uintptr_t)slot;
;     { const bf16* src = Kg + (size_t)(kv0 + lane) * 768 + wave * 8;
;       glds16(src, (unsigned)__builtin_amdgcn_readfirstlane(s0 + wave * 1024));
;       if (wave < 4) glds16(src + 64, (unsigned)__builtin_amdgcn_readfirstlane(s0 + (8 + wave) * 1024)); }
;     { const bf16* src = Vg + (size_t)(kv0 + 16 * (wave & 3) + (lane >> 2)) * 1024 + (wave >> 2) * 32 + (lane & 3) * 8;
;       glds16(src, (unsigned)__builtin_amdgcn_readfirstlane(s0 + KSLOT + wave * 1024)); }
; }
; __device__ __forceinline__ void attn_unit(const bf16* Q, const bf16* K, const bf16* V, bf16* O, int b, int h, int qb, float sref, LAS unsigned char* lds, int wave, int lane_) {
;     ...
;         asm volatile("s_waitcnt vmcnt(0)" ::: "memory"); PA_BAR();
;         if (t + 2 >= NT) break;
;         if (t + 3 < NT) issue_tile(Kg, Vg, lds + sl * SLOT, (t + 3) * 64, wave, lane);
.Lpa1_B_join:
	s_waitcnt lgkmcnt(0)
	s_barrier
	s_andn2_b64 vcc, exec, s[52:53]
	s_cbranch_vccnz .LBB0_1414
	s_cmp_ge_u32 s72, s73
	s_cbranch_scc1 .LBB0_1411
	s_and_b64 vcc, exec, s[2:3]
	s_cbranch_vccnz .LBB0_1411
	v_add_u32_e32 v18, s74, v159
	v_add_u32_e32 v18, 0x100, v18
	v_mov_b64_e32 v[20:21], s[48:49]
	v_mad_i64_i32 v[20:21], s[52:53], v18, s65, v[20:21]
	s_add_i32 s52, s59, s86
	s_add_i32 s98, s72, 1
	s_cmp_ge_u32 s98, s73
	s_cbranch_scc1 .Lpa1_noK
	s_add_i32 s98, s59, s22
	s_mov_b32 s53, m0
	s_mov_b32 m0, s98
	s_nop 0
	global_load_lds_dwordx4 v[20:21], off
	s_mov_b32 m0, s53
	s_and_b64 vcc, exec, s[2:3]
	s_cbranch_vccnz .LBB0_1410
	v_lshl_add_u64 v[20:21], v[20:21], 0, s[30:31]
	s_add_i32 s53, s98, 0x2000
	s_mov_b32 s83, m0
	s_mov_b32 m0, s53
	s_nop 0
	global_load_lds_dwordx4 v[20:21], off
	s_mov_b32 m0, s83

; #define LAS __attribute__((address_space(3)))
; __device__ __forceinline__ void issue_tile(const bf16* Kg, const bf16* Vg, LAS unsigned char* slot, int kv0, int wave, int lane) {
;     const unsigned s0 = (unsigned)(uintptr_t)slot;
;     { const bf16* src = Kg + (size_t)(kv0 + lane) * 768 + wave * 8;
;       glds16(src, (unsigned)__builtin_amdgcn_readfirstlane(s0 + wave * 1024));
;       if (wave < 4) glds16(src + 64, (unsigned)__builtin_amdgcn_readfirstlane(s0 + (8 + wave) * 1024)); }
;     { const bf16* src = Vg + (size_t)(kv0 + 16 * (wave & 3) + (lane >> 2)) * 1024 + (wave >> 2) * 32 + (lane & 3) * 8;
;       glds16(src, (unsigned)__builtin_amdgcn_readfirstlane(s0 + KSLOT + wave * 1024)); }
; }
; __device__ __forceinline__ void attn_unit(const bf16* Q, const bf16* K, const bf16* V, bf16* O, int b, int h, int qb, float sref, LAS unsigned char* lds, int wave, int lane_) {
;     ...
;         if (t + 3 < NT) issue_tile(Kg, Vg, lds + sl * SLOT, (t + 3) * 64, wave, lane);
;         PA_SX(pA0, pA1, t + 2, s2, pB0, pB1); PA_PVN(pB0, pB1, s1);
.LBB0_1413:
	s_and_b64 vcc, exec, s[2:3]
	s_cbranch_vccz .Lpas1_2
	s_cmp_lt_u32 s72, s73
	s_cbranch_scc0 .Lpas1_2
	s_mov_b32 s99, m0
	s_add_i32 s98, s72, 1
	s_cmp_ge_u32 s98, s73
	s_cbranch_scc1 .Lpas1_2v
	v_add_u32_e32 v228, s74, v159
	v_add_u32_e32 v228, 0x100, v228
	v_mov_b64_e32 v[230:231], s[48:49]
	v_mad_i64_i32 v[230:231], s[100:101], v228, s65, v[230:231]
	s_add_i32 s98, s59, s22
	s_mov_b32 m0, s98
	s_nop 0
	global_load_lds_dwordx4 v[230:231], off
.Lpas1_2v:
	s_mul_i32 s98, s84, 0x5000
	s_add_i32 s98, s98, s59
	s_addk_i32 s98, 0x3000
	s_mov_b32 m0, s98
	s_nop 0
	global_load_lds_dwordx4 v[160:161], off
	s_mov_b32 m0, s99

; #define LAS __attribute__((address_space(3)))
; #define PA_BAR() do { asm volatile("s_waitcnt lgkmcnt(0)" ::: "memory"); __builtin_amdgcn_s_barrier(); asm volatile("" ::: "memory"); } while (0)
; __device__ __forceinline__ void issue_tile(const bf16* Kg, const bf16* Vg, LAS unsigned char* slot, int kv0, int wave, int lane) {
;     const unsigned s0 = (unsigned)(uintptr_t)slot;
;     { const bf16* src = Kg + (size_t)(kv0 + lane) * 768 + wave * 8;
;       glds16(src, (unsigned)__builtin_amdgcn_readfirstlane(s0 + wave * 1024));
;       if (wave < 4) glds16(src + 64, (unsigned)__builtin_amdgcn_readfirstlane(s0 + (8 + wave) * 1024)); }
;     { const bf16* src = Vg + (size_t)(kv0 + 16 * (wave & 3) + (lane >> 2)) * 1024 + (wave >> 2) * 32 + (lane & 3) * 8;
;       glds16(src, (unsigned)__builtin_amdgcn_readfirstlane(s0 + KSLOT + wave * 1024)); }
; }
; __device__ __forceinline__ void attn_unit(const bf16* Q, const bf16* K, const bf16* V, bf16* O, int b, int h, int qb, float sref, LAS unsigned char* lds, int wave, int lane_) {
;     ...
;     for (int t = 0; ; t += 2) {
;         const int s2 = (s1 == 2) ? 0 : s1 + 1;
;         asm volatile("s_waitcnt vmcnt(0)" ::: "memory"); PA_BAR();
;         if (t + 2 < NT) issue_tile(Kg, Vg, lds + s2 * SLOT, (t + 2) * 64, wave, lane);
.Lpa2_A_join:
	s_add_i32 s12, s25, 1
	s_cmp_lg_u32 s25, 2
	s_cselect_b32 s12, s12, 0
	s_waitcnt lgkmcnt(0)
	s_barrier
	s_add_i32 s24, s8, -1
	s_cmp_lt_u32 s24, s9
	s_cselect_b64 s[16:17], -1, 0
	s_cmp_ge_u32 s24, s9
	s_mul_i32 s27, s12, 0x5000
	s_cbranch_scc1 .LBB0_1432
	s_and_b64 vcc, exec, s[2:3]
	s_cbranch_vccnz .LBB0_1432
	v_add_u32_e32 v18, s1, v159
	s_add_i32 s22, s27, 0
	v_add_u32_e32 v18, 0xc0, v18
	v_mov_b64_e32 v[20:21], s[48:49]
	v_mad_i64_i32 v[20:21], s[34:35], v18, s65, v[20:21]
	s_add_i32 s22, s59, s22
	s_mul_i32 s98, s26, 0x5000
	s_add_i32 s98, s98, s59
	s_mov_b32 s33, m0
	s_mov_b32 m0, s98
	s_nop 0
	global_load_lds_dwordx4 v[20:21], off
	s_mov_b32 m0, s33
	s_and_b64 vcc, exec, s[2:3]
	s_cbranch_vccnz .LBB0_1431
	v_lshl_add_u64 v[20:21], v[20:21], 0, s[30:31]
	s_add_i32 s33, s98, 0x2000
	s_mov_b32 s34, m0
	s_mov_b32 m0, s33
	s_nop 0
	global_load_lds_dwordx4 v[20:21], off
	s_mov_b32 m0, s34

; #define LAS __attribute__((address_space(3)))
; __device__ __forceinline__ void issue_tile(const bf16* Kg, const bf16* Vg, LAS unsigned char* slot, int kv0, int wave, int lane) {
;     const unsigned s0 = (unsigned)(uintptr_t)slot;
;     { const bf16* src = Kg + (size_t)(kv0 + lane) * 768 + wave * 8;
;       glds16(src, (unsigned)__builtin_amdgcn_readfirstlane(s0 + wave * 1024));
;       if (wave < 4) glds16(src + 64, (unsigned)__builtin_amdgcn_readfirstlane(s0 + (8 + wave) * 1024)); }
;     { const bf16* src = Vg + (size_t)(kv0 + 16 * (wave & 3) + (lane >> 2)) * 1024 + (wave >> 2) * 32 + (lane & 3) * 8;
;       glds16(src, (unsigned)__builtin_amdgcn_readfirstlane(s0 + KSLOT + wave * 1024)); }
; }
.LBB0_1434:
	s_and_b64 vcc, exec, s[2:3]
	s_cbranch_vccz .Lpas2_1
	s_cmp_lt_u32 s24, s9
	s_cbranch_scc0 .Lpas2_1
	v_add_u32_e32 v228, s1, v159
	v_add_u32_e32 v228, 0xc0, v228
	v_mov_b64_e32 v[230:231], s[48:49]
	v_mad_i64_i32 v[230:231], s[100:101], v228, s65, v[230:231]
	s_mul_i32 s98, s26, 0x5000
	s_add_i32 s98, s98, s59
	s_mov_b32 s99, m0
	s_mov_b32 m0, s98
	s_nop 0
	global_load_lds_dwordx4 v[230:231], off
	s_mul_i32 s98, s12, 0x5000
	s_add_i32 s98, s98, s59
	s_addk_i32 s98, 0x3000
	s_mov_b32 m0, s98
	s_nop 0
	global_load_lds_dwordx4 v[162:163], off
	s_mov_b32 m0, s99

; #define LAS __attribute__((address_space(3)))
; #define PA_BAR() do { asm volatile("s_waitcnt lgkmcnt(0)" ::: "memory"); __builtin_amdgcn_s_barrier(); asm volatile("" ::: "memory"); } while (0)
; __device__ __forceinline__ void issue_tile(const bf16* Kg, const bf16* Vg, LAS unsigned char* slot, int kv0, int wave, int lane) {
;     const unsigned s0 = (unsigned)(uintptr_t)slot;
;     { const bf16* src = Kg + (size_t)(kv0 + lane) * 768 + wave * 8;
;       glds16(src, (unsigned)__builtin_amdgcn_readfirstlane(s0 + wave * 1024));
;       if (wave < 4) glds16(src + 64, (unsigned)__builtin_amdgcn_readfirstlane(s0 + (8 + wave) * 1024)); }
;     { const bf16* src = Vg + (size_t)(kv0 + 16 * (wave & 3) + (lane >> 2)) * 1024 + (wave >> 2) * 32 + (lane & 3) * 8;
;       glds16(src, (unsigned)__builtin_amdgcn_readfirstlane(s0 + KSLOT + wave * 1024)); }
; }
; __device__ __forceinline__ void attn_unit(const bf16* Q, const bf16* K, const bf16* V, bf16* O, int b, int h, int qb, float sref, LAS unsigned char* lds, int wave, int lane_) {
;     ...
;         asm volatile("s_waitcnt vmcnt(0)" ::: "memory"); PA_BAR();
;         if (t + 2 >= NT) break;
;         if (t + 3 < NT) issue_tile(Kg, Vg, lds + sl * SLOT, (t + 3) * 64, wave, lane);
.Lpa2_B_join:
	s_waitcnt lgkmcnt(0)
	s_barrier
	s_andn2_b64 vcc, exec, s[16:17]
	s_cbranch_vccnz .LBB0_1442
	s_cmp_ge_u32 s8, s9
	s_cbranch_scc1 .LBB0_1439
	s_and_b64 vcc, exec, s[2:3]
	s_cbranch_vccnz .LBB0_1439
	v_add_u32_e32 v18, s1, v159
	v_add_u32_e32 v18, 0x100, v18
	v_mov_b64_e32 v[20:21], s[48:49]
	v_mad_i64_i32 v[20:21], s[16:17], v18, s65, v[20:21]
	s_add_i32 s16, s59, s33
	s_add_i32 s98, s8, 1
	s_cmp_ge_u32 s98, s9
	s_cbranch_scc1 .Lpa2_noK
	s_add_i32 s98, s59, s22
	s_mov_b32 s17, m0
	s_mov_b32 m0, s98
	s_nop 0
	global_load_lds_dwordx4 v[20:21], off
	s_mov_b32 m0, s17
	s_and_b64 vcc, exec, s[2:3]
	s_cbranch_vccnz .LBB0_1438
	v_lshl_add_u64 v[20:21], v[20:21], 0, s[30:31]
	s_add_i32 s17, s98, 0x2000
	s_mov_b32 s25, m0
	s_mov_b32 m0, s17
	s_nop 0
	global_load_lds_dwordx4 v[20:21], off
	s_mov_b32 m0, s25

; #define LAS __attribute__((address_space(3)))
; __device__ __forceinline__ void issue_tile(const bf16* Kg, const bf16* Vg, LAS unsigned char* slot, int kv0, int wave, int lane) {
;     const unsigned s0 = (unsigned)(uintptr_t)slot;
;     { const bf16* src = Kg + (size_t)(kv0 + lane) * 768 + wave * 8;
;       glds16(src, (unsigned)__builtin_amdgcn_readfirstlane(s0 + wave * 1024));
;       if (wave < 4) glds16(src + 64, (unsigned)__builtin_amdgcn_readfirstlane(s0 + (8 + wave) * 1024)); }
;     { const bf16* src = Vg + (size_t)(kv0 + 16 * (wave & 3) + (lane >> 2)) * 1024 + (wave >> 2) * 32 + (lane & 3) * 8;
;       glds16(src, (unsigned)__builtin_amdgcn_readfirstlane(s0 + KSLOT + wave * 1024)); }
; }
; __device__ __forceinline__ void attn_unit(const bf16* Q, const bf16* K, const bf16* V, bf16* O, int b, int h, int qb, float sref, LAS unsigned char* lds, int wave, int lane_) {
;     ...
;         if (t + 3 < NT) issue_tile(Kg, Vg, lds + sl * SLOT, (t + 3) * 64, wave, lane);
;         PA_SX(pA0, pA1, t + 2, s2, pB0, pB1); PA_PVN(pB0, pB1, s1);
.LBB0_1441:
	s_and_b64 vcc, exec, s[2:3]
	s_cbranch_vccz .Lpas2_2
	s_cmp_lt_u32 s8, s9
	s_cbranch_scc0 .Lpas2_2
	s_mov_b32 s99, m0
	s_add_i32 s98, s8, 1
	s_cmp_ge_u32 s98, s9
	s_cbranch_scc1 .Lpas2_2v
	v_add_u32_e32 v228, s1, v159
	v_add_u32_e32 v228, 0x100, v228
	v_mov_b64_e32 v[230:231], s[48:49]
	v_mad_i64_i32 v[230:231], s[100:101], v228, s65, v[230:231]
	s_add_i32 s98, s59, s22
	s_mov_b32 m0, s98
	s_nop 0
	global_load_lds_dwordx4 v[230:231], off
.Lpas2_2v:
	s_mul_i32 s98, s26, 0x5000
	s_add_i32 s98, s98, s59
	s_addk_i32 s98, 0x3000
	s_mov_b32 m0, s98
	s_nop 0
	global_load_lds_dwordx4 v[160:161], off
	s_mov_b32 m0, s99

; __global__ void __launch_bounds__(NWAVES * 64, 2) mk_fwd(Args args) {
	.amdhsa_kernel _Z6mk_fwd4Args
		.amdhsa_group_segment_fixed_size 0
		.amdhsa_private_segment_fixed_size 0
		.amdhsa_kernarg_size 592
		.amdhsa_user_sgpr_count 2
		.amdhsa_user_sgpr_dispatch_ptr 0
		.amdhsa_user_sgpr_queue_ptr 0
		.amdhsa_user_sgpr_kernarg_segment_ptr 1
		.amdhsa_user_sgpr_dispatch_id 0
		.amdhsa_user_sgpr_kernarg_preload_length 0
		.amdhsa_user_sgpr_kernarg_preload_offset 0
		.amdhsa_user_sgpr_private_segment_size 0
		.amdhsa_uses_dynamic_stack 0
		.amdhsa_enable_private_segment 0
		.amdhsa_system_sgpr_workgroup_id_x 1
		.amdhsa_system_sgpr_workgroup_id_y 0
		.amdhsa_system_sgpr_workgroup_id_z 0
		.amdhsa_system_sgpr_workgroup_info 0
		.amdhsa_system_vgpr_workitem_id 0
		.amdhsa_next_free_vgpr 256
		.amdhsa_next_free_sgpr 102
		.amdhsa_accum_offset 256
		.amdhsa_reserve_vcc 1
		.amdhsa_float_round_mode_32 0
		.amdhsa_float_round_mode_16_64 0
		.amdhsa_float_denorm_mode_32 3
		.amdhsa_float_denorm_mode_16_64 3
		.amdhsa_dx10_clamp 1
		.amdhsa_ieee_mode 1
		.amdhsa_fp16_overflow 0
		.amdhsa_tg_split 0
		.amdhsa_exception_fp_ieee_invalid_op 0
		.amdhsa_exception_fp_denorm_src 0
		.amdhsa_exception_fp_ieee_div_zero 0
		.amdhsa_exception_fp_ieee_overflow 0
		.amdhsa_exception_fp_ieee_underflow 0
		.amdhsa_exception_fp_ieee_inexact 0
		.amdhsa_exception_int_div_zero 0
	.end_amdhsa_kernel

; __global__ void __launch_bounds__(NWAVES * 64, 2) mk_fwd(Args args) {
amdhsa.kernels:
  - .agpr_count:     0
    .args:
      - .offset:         0
        .size:           336
        .value_kind:     by_value
      - .offset:         336
        .size:           4
        .value_kind:     hidden_block_count_x
      - .offset:         340
        .size:           4
        .value_kind:     hidden_block_count_y
      - .offset:         344
        .size:           4
        .value_kind:     hidden_block_count_z
      - .offset:         348
        .size:           2
        .value_kind:     hidden_group_size_x
      - .offset:         350
        .size:           2
        .value_kind:     hidden_group_size_y
      - .offset:         352
        .size:           2
        .value_kind:     hidden_group_size_z
      - .offset:         354
        .size:           2
        .value_kind:     hidden_remainder_x
      - .offset:         356
        .size:           2
        .value_kind:     hidden_remainder_y
      - .offset:         358
        .size:           2
        .value_kind:     hidden_remainder_z
      - .offset:         376
        .size:           8
        .value_kind:     hidden_global_offset_x
      - .offset:         384
        .size:           8
        .value_kind:     hidden_global_offset_y
      - .offset:         392
        .size:           8
        .value_kind:     hidden_global_offset_z
      - .offset:         400
        .size:           2
        .value_kind:     hidden_grid_dims
      - .offset:         456
        .size:           4
        .value_kind:     hidden_dynamic_lds_size
    .group_segment_fixed_size: 0
    .kernarg_segment_align: 8
    .kernarg_segment_size: 592
    .language:       OpenCL C
    .language_version:
      - 2
      - 0
    .max_flat_workgroup_size: 512
    .name:           _Z6mk_fwd4Args
    .private_segment_fixed_size: 0
    .sgpr_count:     108
    .sgpr_spill_count: 132
    .symbol:         _Z6mk_fwd4Args.kd
    .uniform_work_group_size: 1
    .uses_dynamic_stack: false
    .vgpr_count:     256
    .vgpr_spill_count: 0
    .wavefront_size: 64
